# NA attention bias: batched unconditional LDS reads + cndmask instead of 16 serial exec-masked read/wait blocks
# speedup vs baseline: 1.0029x; 1.0029x over previous
.LBB0_1021:
	s_bitcmp1_b32 s0, 0
	s_cselect_b32 s0, 0x8800, 0
	s_add_i32 s87, s0, 0
	s_cmp_ge_i32 s5, s28
	s_cbranch_scc1 .LBB0_1107
	s_cmp_lt_i32 s5, s7
	s_cselect_b64 s[0:1], -1, 0
	s_cmp_ge_i32 s5, s7
	s_cselect_b64 s[2:3], -1, 0
	s_add_i32 s20, s4, s5
	s_add_i32 s20, s20, -4
	v_cmp_ge_u32_e64 s[58:59], s20, v200
	v_cmp_lt_u32_e32 vcc, s20, v201
	s_and_b64 s[56:57], s[58:59], vcc
	s_or_b64 s[56:57], s[2:3], s[56:57]
	s_and_saveexec_b64 s[2:3], s[56:57]
	s_cbranch_execz .LBB0_1102
	v_add_u32_e32 v0, s87, v202
	v_add_u32_e32 v76, v0, v203
	v_add_u32_e32 v0, v0, v204
	ds_read_b128 v[108:111], v76
	ds_read_b128 v[112:115], v76 offset:2048
	ds_read_b128 v[116:119], v76 offset:4096
	ds_read_b128 v[120:123], v76 offset:6144
	ds_read_b128 v[124:127], v0
	ds_read_b128 v[128:131], v0 offset:2048
	ds_read_b128 v[132:135], v0 offset:4096
	ds_read_b128 v[136:139], v0 offset:6144
	v_add3_u32 v0, s87, v199, v205
	v_add_u32_e32 v92, 0x2000, v0
	v_add_u32_e32 v96, 0x2800, v0
	v_add_u32_e32 v100, 0x3000, v0
	v_add_u32_e32 v0, 0x3800, v0
	ds_read2_b64 v[76:79], v92 offset1:4
	ds_read2_b64 v[80:83], v96 offset0:32 offset1:36
	ds_read2_b64 v[84:87], v100 offset0:64 offset1:68
	ds_read2_b64 v[88:91], v0 offset0:96 offset1:100
	ds_read2_b64 v[92:95], v92 offset0:8 offset1:12
	ds_read2_b64 v[96:99], v96 offset0:40 offset1:44
	ds_read2_b64 v[100:103], v100 offset0:72 offset1:76
	ds_read2_b64 v[104:107], v0 offset0:104 offset1:108
	s_waitcnt lgkmcnt(14)
	v_mfma_f32_16x16x32_bf16 v[140:143], v[108:111], v[4:7], 0
	v_mfma_f32_16x16x32_bf16 v[108:111], v[108:111], v[12:15], 0
	v_mfma_f32_16x16x32_bf16 v[144:147], v[112:115], v[4:7], 0
	v_mfma_f32_16x16x32_bf16 v[112:115], v[112:115], v[12:15], 0
	s_waitcnt lgkmcnt(13)
	v_mfma_f32_16x16x32_bf16 v[148:151], v[116:119], v[4:7], 0
	v_mfma_f32_16x16x32_bf16 v[116:119], v[116:119], v[12:15], 0
	s_waitcnt lgkmcnt(12)
	v_mfma_f32_16x16x32_bf16 v[152:155], v[120:123], v[4:7], 0
	v_mfma_f32_16x16x32_bf16 v[120:123], v[120:123], v[12:15], 0
	s_waitcnt lgkmcnt(11)
	v_mfma_f32_16x16x32_bf16 v[140:143], v[124:127], v[8:11], v[140:143]
	v_mfma_f32_16x16x32_bf16 v[108:111], v[124:127], v[16:19], v[108:111]
	s_waitcnt lgkmcnt(10)
	v_mfma_f32_16x16x32_bf16 v[144:147], v[128:131], v[8:11], v[144:147]
	v_mfma_f32_16x16x32_bf16 v[112:115], v[128:131], v[16:19], v[112:115]
	s_waitcnt lgkmcnt(9)
	v_mfma_f32_16x16x32_bf16 v[148:151], v[132:135], v[8:11], v[148:151]
	v_mfma_f32_16x16x32_bf16 v[116:119], v[132:135], v[16:19], v[116:119]
	s_waitcnt lgkmcnt(8)
	v_mfma_f32_16x16x32_bf16 v[152:155], v[136:139], v[8:11], v[152:155]
	v_mfma_f32_16x16x32_bf16 v[120:123], v[136:139], v[16:19], v[120:123]
	v_cndmask_b32_e64 v0, 0, 1, s[0:1]
	v_cmp_ne_u32_e64 s[56:57], 1, v0
	s_andn2_b64 vcc, exec, s[0:1]
	s_mov_b64 s[66:67], -1
	s_cbranch_vccnz .LBB0_1189
	v_add3_u32 v0, v225, s5, -4
	v_max_i32_e32 v0, -7, v0
	v_add_u32_e32 v0, 7, v0
	v_readlane_b32 s65, v254, 35
	v_cmp_lt_u32_e32 vcc, s20, v206
	v_min_u32_e32 v0, 14, v0
	v_mov_b32_e32 v124, s65
	s_movk_i32 s65, 0x7c
	v_mad_u32_u24 v0, v0, s65, v124
	v_lshl_add_u32 v124, v207, 2, v0
	v_lshl_add_u32 v125, v208, 2, v0
	v_lshl_add_u32 v126, v209, 2, v0
	v_lshl_add_u32 v127, v210, 2, v0
	v_lshl_add_u32 v128, v211, 2, v0
	v_lshl_add_u32 v129, v212, 2, v0
	v_lshl_add_u32 v130, v213, 2, v0
	v_lshl_add_u32 v131, v214, 2, v0
	v_lshl_add_u32 v132, v215, 2, v0
	v_lshl_add_u32 v133, v216, 2, v0
	v_lshl_add_u32 v134, v217, 2, v0
	v_lshl_add_u32 v135, v218, 2, v0
	v_lshl_add_u32 v136, v219, 2, v0
	v_lshl_add_u32 v137, v220, 2, v0
	v_lshl_add_u32 v138, v221, 2, v0
	v_lshl_add_u32 v139, v222, 2, v0
	ds_read_b32 v124, v124 offset:60
	ds_read_b32 v125, v125 offset:60
	ds_read_b32 v126, v126 offset:60
	ds_read_b32 v127, v127 offset:60
	ds_read_b32 v128, v128
	ds_read_b32 v129, v129
	ds_read_b32 v130, v130
	ds_read_b32 v131, v131
	ds_read_b32 v132, v132
	ds_read_b32 v133, v133
	ds_read_b32 v134, v134
	ds_read_b32 v135, v135
	ds_read_b32 v136, v136
	ds_read_b32 v137, v137
	ds_read_b32 v138, v138
	ds_read_b32 v139, v139
	s_and_b64 s[58:59], s[58:59], vcc
	v_mov_b32_e32 v0, 0xff800000
	s_and_b64 s[66:67], s[40:41], s[58:59]
	s_waitcnt lgkmcnt(0)
	v_fmac_f32_e32 v124, 0x3e38aa3b, v140
	v_fmac_f32_e32 v125, 0x3e38aa3b, v141
	v_fmac_f32_e32 v126, 0x3e38aa3b, v142
	v_fmac_f32_e32 v127, 0x3e38aa3b, v143
	v_fmac_f32_e32 v128, 0x3e38aa3b, v144
	v_fmac_f32_e32 v129, 0x3e38aa3b, v145
	v_fmac_f32_e32 v130, 0x3e38aa3b, v146
	v_fmac_f32_e32 v131, 0x3e38aa3b, v147
	v_fmac_f32_e32 v132, 0x3e38aa3b, v148
	v_fmac_f32_e32 v133, 0x3e38aa3b, v149
	v_fmac_f32_e32 v134, 0x3e38aa3b, v150
	v_fmac_f32_e32 v135, 0x3e38aa3b, v151
	v_fmac_f32_e32 v136, 0x3e38aa3b, v152
	v_fmac_f32_e32 v137, 0x3e38aa3b, v153
	v_fmac_f32_e32 v138, 0x3e38aa3b, v154
	v_fmac_f32_e32 v139, 0x3e38aa3b, v155
	s_and_b64 s[82:83], s[42:43], s[58:59]
	v_cndmask_b32_e64 v124, v0, v124, s[66:67]
	s_and_b64 s[66:67], s[44:45], s[58:59]
	v_cndmask_b32_e64 v125, v0, v125, s[82:83]
	s_and_b64 s[82:83], s[46:47], s[58:59]
	v_cndmask_b32_e64 v126, v0, v126, s[66:67]
	s_and_b64 s[66:67], s[90:91], s[58:59]
	v_cndmask_b32_e64 v127, v0, v127, s[82:83]
	s_and_b64 s[82:83], s[8:9], s[58:59]
	v_cndmask_b32_e64 v128, v0, v128, s[66:67]
	s_and_b64 s[66:67], s[88:89], s[58:59]
	v_cndmask_b32_e64 v129, v0, v129, s[82:83]
	s_and_b64 s[82:83], s[94:95], s[58:59]
	v_cndmask_b32_e64 v130, v0, v130, s[66:67]
	s_and_b64 s[66:67], s[96:97], s[58:59]
	v_cndmask_b32_e64 v131, v0, v131, s[82:83]
	s_and_b64 s[82:83], s[84:85], s[58:59]
	v_cndmask_b32_e64 v132, v0, v132, s[66:67]
	s_and_b64 s[66:67], s[18:19], s[58:59]
	v_cndmask_b32_e64 v133, v0, v133, s[82:83]
	s_and_b64 s[82:83], s[62:63], s[58:59]
	v_cndmask_b32_e64 v134, v0, v134, s[66:67]
	s_and_b64 s[66:67], s[48:49], s[58:59]
	v_cndmask_b32_e64 v135, v0, v135, s[82:83]
	s_and_b64 s[82:83], s[50:51], s[58:59]
	v_cndmask_b32_e64 v136, v0, v136, s[66:67]
	s_and_b64 s[66:67], s[52:53], s[58:59]
	v_cndmask_b32_e64 v137, v0, v137, s[82:83]
	s_and_b64 s[82:83], s[54:55], s[58:59]
	v_cndmask_b32_e64 v138, v0, v138, s[66:67]
	s_nop 0
	v_cndmask_b32_e64 v139, v0, v139, s[82:83]
	v_max3_f32 v0, v2, v124, v125
	v_max3_f32 v0, v0, v126, v127
	v_max3_f32 v0, v0, v128, v129
	v_max3_f32 v0, v0, v130, v131
	v_max3_f32 v0, v0, v132, v133
	v_max3_f32 v0, v0, v134, v135
	v_max3_f32 v0, v0, v136, v137
	v_max3_f32 v0, v0, v138, v139

.LBB0_1062:
	s_mov_b32 s66, s64
	s_mov_b32 s67, s64
	s_mov_b32 s65, s64
	v_mov_b64_e32 v[134:135], s[66:67]
	v_mov_b64_e32 v[132:133], s[64:65]
	v_exp_f32_e32 v0, v0
	v_cvt_pk_bf16_f32 v128, v140, v141
	v_cvt_pk_bf16_f32 v129, v142, v143
	v_cvt_pk_bf16_f32 v130, v144, v145
	v_cvt_pk_bf16_f32 v131, v146, v147
	v_cvt_pk_bf16_f32 v124, v148, v149
	v_cvt_pk_bf16_f32 v125, v150, v151
	v_mfma_f32_16x16x32_bf16 v[68:71], v[132:135], v[128:131], v[68:71]
	v_cvt_pk_bf16_f32 v126, v152, v153
	v_cvt_pk_bf16_f32 v127, v154, v0
	s_and_b64 vcc, exec, s[56:57]
	s_mov_b64 s[0:1], -1
	v_mfma_f32_16x16x32_bf16 v[68:71], v[132:135], v[124:127], v[68:71]
	s_cbranch_vccnz .LBB0_1192
	v_add3_u32 v0, v225, s5, -5
	v_max_i32_e32 v0, -7, v0
	v_cmp_ge_u32_e32 vcc, s20, v223
	v_cmp_lt_u32_e64 s[0:1], s20, v224
	v_add_u32_e32 v0, 7, v0
	v_readlane_b32 s20, v254, 35
	v_min_u32_e32 v0, 14, v0
	v_mov_b32_e32 v2, s20
	s_movk_i32 s20, 0x7c
	v_mad_u32_u24 v0, v0, s20, v2
	v_lshl_add_u32 v132, v207, 2, v0
	v_lshl_add_u32 v133, v208, 2, v0
	v_lshl_add_u32 v134, v209, 2, v0
	v_lshl_add_u32 v135, v210, 2, v0
	v_lshl_add_u32 v136, v211, 2, v0
	v_lshl_add_u32 v137, v212, 2, v0
	v_lshl_add_u32 v138, v213, 2, v0
	v_lshl_add_u32 v139, v214, 2, v0
	v_lshl_add_u32 v140, v215, 2, v0
	v_lshl_add_u32 v141, v216, 2, v0
	v_lshl_add_u32 v142, v217, 2, v0
	v_lshl_add_u32 v143, v218, 2, v0
	v_lshl_add_u32 v144, v219, 2, v0
	v_lshl_add_u32 v145, v220, 2, v0
	v_lshl_add_u32 v146, v221, 2, v0
	v_lshl_add_u32 v147, v222, 2, v0
	ds_read_b32 v132, v132 offset:60
	ds_read_b32 v133, v133 offset:60
	ds_read_b32 v134, v134 offset:60
	ds_read_b32 v135, v135 offset:60
	ds_read_b32 v136, v136
	ds_read_b32 v137, v137
	ds_read_b32 v138, v138
	ds_read_b32 v139, v139
	ds_read_b32 v140, v140
	ds_read_b32 v141, v141
	ds_read_b32 v142, v142
	ds_read_b32 v143, v143
	ds_read_b32 v144, v144
	ds_read_b32 v145, v145
	ds_read_b32 v146, v146
	ds_read_b32 v147, v147
	s_and_b64 s[0:1], s[0:1], vcc
	v_mov_b32_e32 v0, 0xff800000
	s_and_b64 s[58:59], s[40:41], s[0:1]
	s_waitcnt lgkmcnt(0)
	v_fmac_f32_e32 v132, 0x3e38aa3b, v108
	v_fmac_f32_e32 v133, 0x3e38aa3b, v109
	v_fmac_f32_e32 v134, 0x3e38aa3b, v110
	v_fmac_f32_e32 v135, 0x3e38aa3b, v111
	v_fmac_f32_e32 v136, 0x3e38aa3b, v112
	v_fmac_f32_e32 v137, 0x3e38aa3b, v113
	v_fmac_f32_e32 v138, 0x3e38aa3b, v114
	v_fmac_f32_e32 v139, 0x3e38aa3b, v115
	v_fmac_f32_e32 v140, 0x3e38aa3b, v116
	v_fmac_f32_e32 v141, 0x3e38aa3b, v117
	v_fmac_f32_e32 v142, 0x3e38aa3b, v118
	v_fmac_f32_e32 v143, 0x3e38aa3b, v119
	v_fmac_f32_e32 v144, 0x3e38aa3b, v120
	v_fmac_f32_e32 v145, 0x3e38aa3b, v121
	v_fmac_f32_e32 v146, 0x3e38aa3b, v122
	v_fmac_f32_e32 v147, 0x3e38aa3b, v123
	s_and_b64 s[66:67], s[42:43], s[0:1]
	v_cndmask_b32_e64 v132, v0, v132, s[58:59]
	s_and_b64 s[58:59], s[44:45], s[0:1]
	v_cndmask_b32_e64 v133, v0, v133, s[66:67]
	s_and_b64 s[66:67], s[46:47], s[0:1]
	v_cndmask_b32_e64 v134, v0, v134, s[58:59]
	s_and_b64 s[58:59], s[90:91], s[0:1]
	v_cndmask_b32_e64 v135, v0, v135, s[66:67]
	s_and_b64 s[66:67], s[8:9], s[0:1]
	v_cndmask_b32_e64 v136, v0, v136, s[58:59]
	s_and_b64 s[58:59], s[88:89], s[0:1]
	v_cndmask_b32_e64 v137, v0, v137, s[66:67]
	s_and_b64 s[66:67], s[94:95], s[0:1]
	v_cndmask_b32_e64 v138, v0, v138, s[58:59]
	s_and_b64 s[58:59], s[96:97], s[0:1]
	v_cndmask_b32_e64 v139, v0, v139, s[66:67]
	s_and_b64 s[66:67], s[84:85], s[0:1]
	v_cndmask_b32_e64 v140, v0, v140, s[58:59]
	s_and_b64 s[58:59], s[18:19], s[0:1]
	v_cndmask_b32_e64 v141, v0, v141, s[66:67]
	s_and_b64 s[66:67], s[62:63], s[0:1]
	v_cndmask_b32_e64 v142, v0, v142, s[58:59]
	s_and_b64 s[58:59], s[48:49], s[0:1]
	v_cndmask_b32_e64 v143, v0, v143, s[66:67]
	s_and_b64 s[66:67], s[50:51], s[0:1]
	v_cndmask_b32_e64 v144, v0, v144, s[58:59]
	s_and_b64 s[58:59], s[52:53], s[0:1]
	v_cndmask_b32_e64 v145, v0, v145, s[66:67]
	s_and_b64 s[66:67], s[54:55], s[0:1]
	v_cndmask_b32_e64 v146, v0, v146, s[58:59]
	s_nop 0
	v_cndmask_b32_e64 v147, v0, v147, s[66:67]
	v_max3_f32 v0, v165, v132, v133
	v_max3_f32 v0, v0, v134, v135
	v_max3_f32 v0, v0, v136, v137
	v_max3_f32 v0, v0, v138, v139
	v_max3_f32 v0, v0, v140, v141
	v_max3_f32 v0, v0, v142, v143
	v_max3_f32 v0, v0, v144, v145
	v_max3_f32 v0, v0, v146, v147

.LBB0_1108:
	s_cmp_lt_i32 s2, s7
	s_cselect_b64 s[0:1], -1, 0
	s_cmp_ge_i32 s2, s7
	s_cselect_b64 s[2:3], -1, 0
	s_add_i32 s20, s4, s5
	s_add_i32 s20, s20, -3
	v_cmp_ge_u32_e64 s[58:59], s20, v200
	v_cmp_lt_u32_e32 vcc, s20, v201
	s_and_b64 s[56:57], s[58:59], vcc
	s_or_b64 s[56:57], s[2:3], s[56:57]
	s_and_saveexec_b64 s[2:3], s[56:57]
	s_cbranch_execz .LBB0_1188
	v_add_u32_e32 v0, s87, v202
	v_add_u32_e32 v76, v0, v203
	v_add_u32_e32 v0, v0, v204
	ds_read_b128 v[108:111], v76 offset:17408
	ds_read_b128 v[112:115], v76 offset:19456
	ds_read_b128 v[116:119], v76 offset:21504
	ds_read_b128 v[120:123], v76 offset:23552
	ds_read_b128 v[124:127], v0 offset:17408
	ds_read_b128 v[128:131], v0 offset:19456
	ds_read_b128 v[132:135], v0 offset:21504
	ds_read_b128 v[136:139], v0 offset:23552
	v_add3_u32 v0, s87, v199, v205
	v_add_u32_e32 v92, 0x6000, v0
	v_add_u32_e32 v96, 0x6800, v0
	v_add_u32_e32 v100, 0x7000, v0
	v_add_u32_e32 v0, 0x7800, v0
	ds_read2_b64 v[76:79], v92 offset0:128 offset1:132
	ds_read2_b64 v[80:83], v96 offset0:160 offset1:164
	ds_read2_b64 v[84:87], v100 offset0:192 offset1:196
	ds_read2_b64 v[88:91], v0 offset0:224 offset1:228
	ds_read2_b64 v[92:95], v92 offset0:136 offset1:140
	ds_read2_b64 v[96:99], v96 offset0:168 offset1:172
	ds_read2_b64 v[100:103], v100 offset0:200 offset1:204
	ds_read2_b64 v[104:107], v0 offset0:232 offset1:236
	s_waitcnt lgkmcnt(14)
	v_mfma_f32_16x16x32_bf16 v[140:143], v[108:111], v[4:7], 0
	v_mfma_f32_16x16x32_bf16 v[108:111], v[108:111], v[12:15], 0
	v_mfma_f32_16x16x32_bf16 v[144:147], v[112:115], v[4:7], 0
	v_mfma_f32_16x16x32_bf16 v[112:115], v[112:115], v[12:15], 0
	s_waitcnt lgkmcnt(13)
	v_mfma_f32_16x16x32_bf16 v[148:151], v[116:119], v[4:7], 0
	v_mfma_f32_16x16x32_bf16 v[116:119], v[116:119], v[12:15], 0
	s_waitcnt lgkmcnt(12)
	v_mfma_f32_16x16x32_bf16 v[152:155], v[120:123], v[4:7], 0
	v_mfma_f32_16x16x32_bf16 v[120:123], v[120:123], v[12:15], 0
	s_waitcnt lgkmcnt(11)
	v_mfma_f32_16x16x32_bf16 v[140:143], v[124:127], v[8:11], v[140:143]
	v_mfma_f32_16x16x32_bf16 v[108:111], v[124:127], v[16:19], v[108:111]
	s_waitcnt lgkmcnt(10)
	v_mfma_f32_16x16x32_bf16 v[144:147], v[128:131], v[8:11], v[144:147]
	v_mfma_f32_16x16x32_bf16 v[112:115], v[128:131], v[16:19], v[112:115]
	s_waitcnt lgkmcnt(9)
	v_mfma_f32_16x16x32_bf16 v[148:151], v[132:135], v[8:11], v[148:151]
	v_mfma_f32_16x16x32_bf16 v[116:119], v[132:135], v[16:19], v[116:119]
	s_waitcnt lgkmcnt(8)
	v_mfma_f32_16x16x32_bf16 v[152:155], v[136:139], v[8:11], v[152:155]
	v_mfma_f32_16x16x32_bf16 v[120:123], v[136:139], v[16:19], v[120:123]
	v_cndmask_b32_e64 v0, 0, 1, s[0:1]
	v_cmp_ne_u32_e64 s[56:57], 1, v0
	s_andn2_b64 vcc, exec, s[0:1]
	s_mov_b64 s[0:1], -1
	s_cbranch_vccnz .LBB0_1195
	v_add3_u32 v0, v225, s5, -3
	v_max_i32_e32 v0, -7, v0
	v_add_u32_e32 v0, 7, v0
	v_readlane_b32 s0, v254, 35
	v_min_u32_e32 v0, 14, v0
	v_cmp_lt_u32_e32 vcc, s20, v206
	v_mov_b32_e32 v124, s0
	s_movk_i32 s0, 0x7c
	v_mad_u32_u24 v0, v0, s0, v124
	v_lshl_add_u32 v124, v207, 2, v0
	v_lshl_add_u32 v125, v208, 2, v0
	v_lshl_add_u32 v126, v209, 2, v0
	v_lshl_add_u32 v127, v210, 2, v0
	v_lshl_add_u32 v128, v211, 2, v0
	v_lshl_add_u32 v129, v212, 2, v0
	v_lshl_add_u32 v130, v213, 2, v0
	v_lshl_add_u32 v131, v214, 2, v0
	v_lshl_add_u32 v132, v215, 2, v0
	v_lshl_add_u32 v133, v216, 2, v0
	v_lshl_add_u32 v134, v217, 2, v0
	v_lshl_add_u32 v135, v218, 2, v0
	v_lshl_add_u32 v136, v219, 2, v0
	v_lshl_add_u32 v137, v220, 2, v0
	v_lshl_add_u32 v138, v221, 2, v0
	v_lshl_add_u32 v139, v222, 2, v0
	ds_read_b32 v124, v124 offset:60
	ds_read_b32 v125, v125 offset:60
	ds_read_b32 v126, v126 offset:60
	ds_read_b32 v127, v127 offset:60
	ds_read_b32 v128, v128
	ds_read_b32 v129, v129
	ds_read_b32 v130, v130
	ds_read_b32 v131, v131
	ds_read_b32 v132, v132
	ds_read_b32 v133, v133
	ds_read_b32 v134, v134
	ds_read_b32 v135, v135
	ds_read_b32 v136, v136
	ds_read_b32 v137, v137
	ds_read_b32 v138, v138
	ds_read_b32 v139, v139
	s_and_b64 s[58:59], s[58:59], vcc
	v_mov_b32_e32 v0, 0xff800000
	s_and_b64 s[0:1], s[40:41], s[58:59]
	s_waitcnt lgkmcnt(0)
	v_fmac_f32_e32 v124, 0x3e38aa3b, v140
	v_fmac_f32_e32 v125, 0x3e38aa3b, v141
	v_fmac_f32_e32 v126, 0x3e38aa3b, v142
	v_fmac_f32_e32 v127, 0x3e38aa3b, v143
	v_fmac_f32_e32 v128, 0x3e38aa3b, v144
	v_fmac_f32_e32 v129, 0x3e38aa3b, v145
	v_fmac_f32_e32 v130, 0x3e38aa3b, v146
	v_fmac_f32_e32 v131, 0x3e38aa3b, v147
	v_fmac_f32_e32 v132, 0x3e38aa3b, v148
	v_fmac_f32_e32 v133, 0x3e38aa3b, v149
	v_fmac_f32_e32 v134, 0x3e38aa3b, v150
	v_fmac_f32_e32 v135, 0x3e38aa3b, v151
	v_fmac_f32_e32 v136, 0x3e38aa3b, v152
	v_fmac_f32_e32 v137, 0x3e38aa3b, v153
	v_fmac_f32_e32 v138, 0x3e38aa3b, v154
	v_fmac_f32_e32 v139, 0x3e38aa3b, v155
	s_and_b64 s[66:67], s[42:43], s[58:59]
	v_cndmask_b32_e64 v124, v0, v124, s[0:1]
	s_and_b64 s[0:1], s[44:45], s[58:59]
	v_cndmask_b32_e64 v125, v0, v125, s[66:67]
	s_and_b64 s[66:67], s[46:47], s[58:59]
	v_cndmask_b32_e64 v126, v0, v126, s[0:1]
	s_and_b64 s[0:1], s[90:91], s[58:59]
	v_cndmask_b32_e64 v127, v0, v127, s[66:67]
	s_and_b64 s[66:67], s[8:9], s[58:59]
	v_cndmask_b32_e64 v128, v0, v128, s[0:1]
	s_and_b64 s[0:1], s[88:89], s[58:59]
	v_cndmask_b32_e64 v129, v0, v129, s[66:67]
	s_and_b64 s[66:67], s[94:95], s[58:59]
	v_cndmask_b32_e64 v130, v0, v130, s[0:1]
	s_and_b64 s[0:1], s[96:97], s[58:59]
	v_cndmask_b32_e64 v131, v0, v131, s[66:67]
	s_and_b64 s[66:67], s[84:85], s[58:59]
	v_cndmask_b32_e64 v132, v0, v132, s[0:1]
	s_and_b64 s[0:1], s[18:19], s[58:59]
	v_cndmask_b32_e64 v133, v0, v133, s[66:67]
	s_and_b64 s[66:67], s[62:63], s[58:59]
	v_cndmask_b32_e64 v134, v0, v134, s[0:1]
	s_and_b64 s[0:1], s[48:49], s[58:59]
	v_cndmask_b32_e64 v135, v0, v135, s[66:67]
	s_and_b64 s[66:67], s[50:51], s[58:59]
	v_cndmask_b32_e64 v136, v0, v136, s[0:1]
	s_and_b64 s[0:1], s[52:53], s[58:59]
	v_cndmask_b32_e64 v137, v0, v137, s[66:67]
	s_and_b64 s[66:67], s[54:55], s[58:59]
	v_cndmask_b32_e64 v138, v0, v138, s[0:1]
	s_nop 0
	v_cndmask_b32_e64 v139, v0, v139, s[66:67]
	v_max3_f32 v0, v2, v124, v125
	v_max3_f32 v0, v0, v126, v127
	v_max3_f32 v0, v0, v128, v129
	v_max3_f32 v0, v0, v130, v131
	v_max3_f32 v0, v0, v132, v133
	v_max3_f32 v0, v0, v134, v135
	v_max3_f32 v0, v0, v136, v137
	v_max3_f32 v0, v0, v138, v139

.LBB0_1148:
	s_mov_b32 s66, s64
	s_mov_b32 s67, s64
	s_mov_b32 s65, s64
	v_mov_b64_e32 v[134:135], s[66:67]
	v_mov_b64_e32 v[132:133], s[64:65]
	v_exp_f32_e32 v0, v0
	v_cvt_pk_bf16_f32 v128, v140, v141
	v_cvt_pk_bf16_f32 v129, v142, v143
	v_cvt_pk_bf16_f32 v130, v144, v145
	v_cvt_pk_bf16_f32 v131, v146, v147
	v_cvt_pk_bf16_f32 v124, v148, v149
	v_cvt_pk_bf16_f32 v125, v150, v151
	v_mfma_f32_16x16x32_bf16 v[68:71], v[132:135], v[128:131], v[68:71]
	v_cvt_pk_bf16_f32 v126, v152, v153
	v_cvt_pk_bf16_f32 v127, v154, v0
	s_and_b64 vcc, exec, s[56:57]
	s_mov_b64 s[0:1], -1
	v_mfma_f32_16x16x32_bf16 v[68:71], v[132:135], v[124:127], v[68:71]
	s_cbranch_vccnz .LBB0_1198
	v_add3_u32 v0, v225, s5, -4
	v_max_i32_e32 v0, -7, v0
	v_cmp_ge_u32_e32 vcc, s20, v223
	v_cmp_lt_u32_e64 s[0:1], s20, v224
	v_add_u32_e32 v0, 7, v0
	v_readlane_b32 s20, v254, 35
	v_min_u32_e32 v0, 14, v0
	v_mov_b32_e32 v2, s20
	s_movk_i32 s20, 0x7c
	v_mad_u32_u24 v0, v0, s20, v2
	v_lshl_add_u32 v132, v207, 2, v0
	v_lshl_add_u32 v133, v208, 2, v0
	v_lshl_add_u32 v134, v209, 2, v0
	v_lshl_add_u32 v135, v210, 2, v0
	v_lshl_add_u32 v136, v211, 2, v0
	v_lshl_add_u32 v137, v212, 2, v0
	v_lshl_add_u32 v138, v213, 2, v0
	v_lshl_add_u32 v139, v214, 2, v0
	v_lshl_add_u32 v140, v215, 2, v0
	v_lshl_add_u32 v141, v216, 2, v0
	v_lshl_add_u32 v142, v217, 2, v0
	v_lshl_add_u32 v143, v218, 2, v0
	v_lshl_add_u32 v144, v219, 2, v0
	v_lshl_add_u32 v145, v220, 2, v0
	v_lshl_add_u32 v146, v221, 2, v0
	v_lshl_add_u32 v147, v222, 2, v0
	ds_read_b32 v132, v132 offset:60
	ds_read_b32 v133, v133 offset:60
	ds_read_b32 v134, v134 offset:60
	ds_read_b32 v135, v135 offset:60
	ds_read_b32 v136, v136
	ds_read_b32 v137, v137
	ds_read_b32 v138, v138
	ds_read_b32 v139, v139
	ds_read_b32 v140, v140
	ds_read_b32 v141, v141
	ds_read_b32 v142, v142
	ds_read_b32 v143, v143
	ds_read_b32 v144, v144
	ds_read_b32 v145, v145
	ds_read_b32 v146, v146
	ds_read_b32 v147, v147
	s_and_b64 s[0:1], s[0:1], vcc
	v_mov_b32_e32 v0, 0xff800000
	s_and_b64 s[58:59], s[40:41], s[0:1]
	s_waitcnt lgkmcnt(0)
	v_fmac_f32_e32 v132, 0x3e38aa3b, v108
	v_fmac_f32_e32 v133, 0x3e38aa3b, v109
	v_fmac_f32_e32 v134, 0x3e38aa3b, v110
	v_fmac_f32_e32 v135, 0x3e38aa3b, v111
	v_fmac_f32_e32 v136, 0x3e38aa3b, v112
	v_fmac_f32_e32 v137, 0x3e38aa3b, v113
	v_fmac_f32_e32 v138, 0x3e38aa3b, v114
	v_fmac_f32_e32 v139, 0x3e38aa3b, v115
	v_fmac_f32_e32 v140, 0x3e38aa3b, v116
	v_fmac_f32_e32 v141, 0x3e38aa3b, v117
	v_fmac_f32_e32 v142, 0x3e38aa3b, v118
	v_fmac_f32_e32 v143, 0x3e38aa3b, v119
	v_fmac_f32_e32 v144, 0x3e38aa3b, v120
	v_fmac_f32_e32 v145, 0x3e38aa3b, v121
	v_fmac_f32_e32 v146, 0x3e38aa3b, v122
	v_fmac_f32_e32 v147, 0x3e38aa3b, v123
	s_and_b64 s[66:67], s[42:43], s[0:1]
	v_cndmask_b32_e64 v132, v0, v132, s[58:59]
	s_and_b64 s[58:59], s[44:45], s[0:1]
	v_cndmask_b32_e64 v133, v0, v133, s[66:67]
	s_and_b64 s[66:67], s[46:47], s[0:1]
	v_cndmask_b32_e64 v134, v0, v134, s[58:59]
	s_and_b64 s[58:59], s[90:91], s[0:1]
	v_cndmask_b32_e64 v135, v0, v135, s[66:67]
	s_and_b64 s[66:67], s[8:9], s[0:1]
	v_cndmask_b32_e64 v136, v0, v136, s[58:59]
	s_and_b64 s[58:59], s[88:89], s[0:1]
	v_cndmask_b32_e64 v137, v0, v137, s[66:67]
	s_and_b64 s[66:67], s[94:95], s[0:1]
	v_cndmask_b32_e64 v138, v0, v138, s[58:59]
	s_and_b64 s[58:59], s[96:97], s[0:1]
	v_cndmask_b32_e64 v139, v0, v139, s[66:67]
	s_and_b64 s[66:67], s[84:85], s[0:1]
	v_cndmask_b32_e64 v140, v0, v140, s[58:59]
	s_and_b64 s[58:59], s[18:19], s[0:1]
	v_cndmask_b32_e64 v141, v0, v141, s[66:67]
	s_and_b64 s[66:67], s[62:63], s[0:1]
	v_cndmask_b32_e64 v142, v0, v142, s[58:59]
	s_and_b64 s[58:59], s[48:49], s[0:1]
	v_cndmask_b32_e64 v143, v0, v143, s[66:67]
	s_and_b64 s[66:67], s[50:51], s[0:1]
	v_cndmask_b32_e64 v144, v0, v144, s[58:59]
	s_and_b64 s[58:59], s[52:53], s[0:1]
	v_cndmask_b32_e64 v145, v0, v145, s[66:67]
	s_and_b64 s[66:67], s[54:55], s[0:1]
	v_cndmask_b32_e64 v146, v0, v146, s[58:59]
	s_nop 0
	v_cndmask_b32_e64 v147, v0, v147, s[66:67]
	v_max3_f32 v0, v165, v132, v133
	v_max3_f32 v0, v0, v134, v135
	v_max3_f32 v0, v0, v136, v137
	v_max3_f32 v0, v0, v138, v139
	v_max3_f32 v0, v0, v140, v141
	v_max3_f32 v0, v0, v142, v143
	v_max3_f32 v0, v0, v144, v145
	v_max3_f32 v0, v0, v146, v147
